# nt on the gla_pass2 chunk-state (U) loads so the shared decay table stays in L2
# speedup vs baseline: 1.0050x; 1.0050x over previous
; __device__ __forceinline__ void gla_pass2(const Ctx& cx, const Params& p) {
;     ...
;   for (int idx = cx.vb * NT + cx.tid; idx < 128 * 1024; idx += cx.vg * NT) {
;     const int c = idx >> 10, e4 = idx & 1023, d0 = (4 * e4) & 63;
;     f32x4 S = (f32x4){0.f, 0.f, 0.f, 0.f};
; #pragma unroll 4
;     for (int n = 0; n < 36; ++n) {
;       const size_t o = ((size_t)(c * 36 + n) << 10) + e4;
;       const u32x2 uu = U[o];
;       const f32x4 gg = *reinterpret_cast<const f32x4*>(G + (size_t)(c * 36 + n) * 64 + d0);
;       U[o] = (u32x2){pack2(S[0], S[1]), pack2(S[2], S[3])};
;       const f32x4 uv = (f32x4){__uint_as_float(uu.x << 16), __uint_as_float(uu.x & 0xffff0000u), __uint_as_float(uu.y << 16), __uint_as_float(uu.y & 0xffff0000u)};
;       S = gg * S + uv;
;     }
;   }
.Lp2_batch:
	s_mov_b64 s[12:13], 0x1000
	v_mov_b32_e32 v22, v10
	v_mov_b32_e32 v23, v11
	v_lshl_add_u64 v[6:7], v[8:9], 0, s[12:13]
	global_load_dwordx2 v[24:25], v[22:23], off nt
	global_load_dwordx4 v[60:63], v[8:9], off
	v_lshl_add_u64 v[22:23], v[22:23], 0, s[10:11]
	global_load_dwordx2 v[26:27], v[22:23], off nt
	global_load_dwordx4 v[64:67], v[8:9], off offset:256
	v_lshl_add_u64 v[22:23], v[22:23], 0, s[10:11]
	global_load_dwordx2 v[28:29], v[22:23], off nt
	global_load_dwordx4 v[68:71], v[8:9], off offset:512
	v_lshl_add_u64 v[22:23], v[22:23], 0, s[10:11]
	global_load_dwordx2 v[30:31], v[22:23], off nt
	global_load_dwordx4 v[72:75], v[8:9], off offset:768
	v_lshl_add_u64 v[22:23], v[22:23], 0, s[10:11]
	global_load_dwordx2 v[32:33], v[22:23], off nt
	global_load_dwordx4 v[76:79], v[8:9], off offset:1024
	v_lshl_add_u64 v[22:23], v[22:23], 0, s[10:11]
	global_load_dwordx2 v[34:35], v[22:23], off nt
	global_load_dwordx4 v[80:83], v[8:9], off offset:1280
	v_lshl_add_u64 v[22:23], v[22:23], 0, s[10:11]
	global_load_dwordx2 v[36:37], v[22:23], off nt
	global_load_dwordx4 v[84:87], v[8:9], off offset:1536
	v_lshl_add_u64 v[22:23], v[22:23], 0, s[10:11]
	global_load_dwordx2 v[38:39], v[22:23], off nt
	global_load_dwordx4 v[88:91], v[8:9], off offset:1792
	v_lshl_add_u64 v[22:23], v[22:23], 0, s[10:11]
	global_load_dwordx2 v[40:41], v[22:23], off nt
	global_load_dwordx4 v[92:95], v[8:9], off offset:2048
	v_lshl_add_u64 v[22:23], v[22:23], 0, s[10:11]
	global_load_dwordx2 v[42:43], v[22:23], off nt
	global_load_dwordx4 v[96:99], v[8:9], off offset:2304
	v_lshl_add_u64 v[22:23], v[22:23], 0, s[10:11]
	global_load_dwordx2 v[44:45], v[22:23], off nt
	global_load_dwordx4 v[100:103], v[8:9], off offset:2560
	v_lshl_add_u64 v[22:23], v[22:23], 0, s[10:11]
	global_load_dwordx2 v[46:47], v[22:23], off nt
	global_load_dwordx4 v[104:107], v[8:9], off offset:2816
	v_lshl_add_u64 v[22:23], v[22:23], 0, s[10:11]
	global_load_dwordx2 v[48:49], v[22:23], off nt
	global_load_dwordx4 v[108:111], v[8:9], off offset:3072
	v_lshl_add_u64 v[22:23], v[22:23], 0, s[10:11]
	global_load_dwordx2 v[50:51], v[22:23], off nt
	global_load_dwordx4 v[112:115], v[8:9], off offset:3328
	v_lshl_add_u64 v[22:23], v[22:23], 0, s[10:11]
	global_load_dwordx2 v[52:53], v[22:23], off nt
	global_load_dwordx4 v[116:119], v[8:9], off offset:3584
	v_lshl_add_u64 v[22:23], v[22:23], 0, s[10:11]
	global_load_dwordx2 v[54:55], v[22:23], off nt
	global_load_dwordx4 v[120:123], v[8:9], off offset:3840
	v_lshl_add_u64 v[22:23], v[22:23], 0, s[10:11]
	global_load_dwordx2 v[56:57], v[22:23], off nt
	global_load_dwordx4 v[124:127], v[6:7], off
	v_lshl_add_u64 v[22:23], v[22:23], 0, s[10:11]
	global_load_dwordx2 v[58:59], v[22:23], off nt
	global_load_dwordx4 v[128:131], v[6:7], off offset:256
	s_waitcnt vmcnt(34)
	v_lshlrev_b32_e32 v2, 16, v24
	v_and_b32_e32 v3, 0xffff0000, v24
	v_lshlrev_b32_e32 v4, 16, v25
	v_and_b32_e32 v5, 0xffff0000, v25
	v_cvt_pk_bf16_f32 v6, v12, v13
	v_cvt_pk_bf16_f32 v7, v14, v15
	v_pk_fma_f32 v[12:13], v[12:13], v[60:61], v[2:3]
	v_pk_fma_f32 v[14:15], v[14:15], v[62:63], v[4:5]
	s_waitcnt vmcnt(32)
	v_lshlrev_b32_e32 v2, 16, v26
	v_and_b32_e32 v3, 0xffff0000, v26
	v_lshlrev_b32_e32 v4, 16, v27
	v_and_b32_e32 v5, 0xffff0000, v27
	v_cvt_pk_bf16_f32 v24, v12, v13
	v_cvt_pk_bf16_f32 v25, v14, v15
	v_pk_fma_f32 v[12:13], v[12:13], v[64:65], v[2:3]
	v_pk_fma_f32 v[14:15], v[14:15], v[66:67], v[4:5]
	s_waitcnt vmcnt(30)
	v_lshlrev_b32_e32 v2, 16, v28
	v_and_b32_e32 v3, 0xffff0000, v28
	v_lshlrev_b32_e32 v4, 16, v29
	v_and_b32_e32 v5, 0xffff0000, v29
	v_cvt_pk_bf16_f32 v26, v12, v13
	v_cvt_pk_bf16_f32 v27, v14, v15
	v_pk_fma_f32 v[12:13], v[12:13], v[68:69], v[2:3]
	v_pk_fma_f32 v[14:15], v[14:15], v[70:71], v[4:5]
	s_waitcnt vmcnt(28)
	v_lshlrev_b32_e32 v2, 16, v30
	v_and_b32_e32 v3, 0xffff0000, v30
	v_lshlrev_b32_e32 v4, 16, v31
	v_and_b32_e32 v5, 0xffff0000, v31
	v_cvt_pk_bf16_f32 v28, v12, v13
	v_cvt_pk_bf16_f32 v29, v14, v15
	v_pk_fma_f32 v[12:13], v[12:13], v[72:73], v[2:3]
	v_pk_fma_f32 v[14:15], v[14:15], v[74:75], v[4:5]
	s_waitcnt vmcnt(26)
	v_lshlrev_b32_e32 v2, 16, v32
	v_and_b32_e32 v3, 0xffff0000, v32
	v_lshlrev_b32_e32 v4, 16, v33
	v_and_b32_e32 v5, 0xffff0000, v33
	v_cvt_pk_bf16_f32 v30, v12, v13
	v_cvt_pk_bf16_f32 v31, v14, v15
	v_pk_fma_f32 v[12:13], v[12:13], v[76:77], v[2:3]
	v_pk_fma_f32 v[14:15], v[14:15], v[78:79], v[4:5]
	s_waitcnt vmcnt(24)
	v_lshlrev_b32_e32 v2, 16, v34
	v_and_b32_e32 v3, 0xffff0000, v34
	v_lshlrev_b32_e32 v4, 16, v35
	v_and_b32_e32 v5, 0xffff0000, v35
	v_cvt_pk_bf16_f32 v32, v12, v13
	v_cvt_pk_bf16_f32 v33, v14, v15
	v_pk_fma_f32 v[12:13], v[12:13], v[80:81], v[2:3]
	v_pk_fma_f32 v[14:15], v[14:15], v[82:83], v[4:5]
	s_waitcnt vmcnt(22)
	v_lshlrev_b32_e32 v2, 16, v36
	v_and_b32_e32 v3, 0xffff0000, v36
	v_lshlrev_b32_e32 v4, 16, v37
	v_and_b32_e32 v5, 0xffff0000, v37
	v_cvt_pk_bf16_f32 v34, v12, v13
	v_cvt_pk_bf16_f32 v35, v14, v15
	v_pk_fma_f32 v[12:13], v[12:13], v[84:85], v[2:3]
	v_pk_fma_f32 v[14:15], v[14:15], v[86:87], v[4:5]
	s_waitcnt vmcnt(20)
	v_lshlrev_b32_e32 v2, 16, v38
	v_and_b32_e32 v3, 0xffff0000, v38
	v_lshlrev_b32_e32 v4, 16, v39
	v_and_b32_e32 v5, 0xffff0000, v39
	v_cvt_pk_bf16_f32 v36, v12, v13
	v_cvt_pk_bf16_f32 v37, v14, v15
	v_pk_fma_f32 v[12:13], v[12:13], v[88:89], v[2:3]
	v_pk_fma_f32 v[14:15], v[14:15], v[90:91], v[4:5]
	s_waitcnt vmcnt(18)
; __device__ __forceinline__ void gla_pass2(const Ctx& cx, const Params& p) {
;     ...
;   for (int idx = cx.vb * NT + cx.tid; idx < 128 * 1024; idx += cx.vg * NT) {
;     ...
;     for (int n = 0; n < 36; ++n) {
;       const size_t o = ((size_t)(c * 36 + n) << 10) + e4;
;       const u32x2 uu = U[o];
;       const f32x4 gg = *reinterpret_cast<const f32x4*>(G + (size_t)(c * 36 + n) * 64 + d0);
;       U[o] = (u32x2){pack2(S[0], S[1]), pack2(S[2], S[3])};
;       const f32x4 uv = (f32x4){__uint_as_float(uu.x << 16), __uint_as_float(uu.x & 0xffff0000u), __uint_as_float(uu.y << 16), __uint_as_float(uu.y & 0xffff0000u)};
;       S = gg * S + uv;
;     }
;   }
	v_lshlrev_b32_e32 v2, 16, v40
	v_and_b32_e32 v3, 0xffff0000, v40
	v_lshlrev_b32_e32 v4, 16, v41
	v_and_b32_e32 v5, 0xffff0000, v41
	v_cvt_pk_bf16_f32 v38, v12, v13
	v_cvt_pk_bf16_f32 v39, v14, v15
	v_pk_fma_f32 v[12:13], v[12:13], v[92:93], v[2:3]
	v_pk_fma_f32 v[14:15], v[14:15], v[94:95], v[4:5]
	s_waitcnt vmcnt(16)
	v_lshlrev_b32_e32 v2, 16, v42
	v_and_b32_e32 v3, 0xffff0000, v42
	v_lshlrev_b32_e32 v4, 16, v43
	v_and_b32_e32 v5, 0xffff0000, v43
	v_cvt_pk_bf16_f32 v40, v12, v13
	v_cvt_pk_bf16_f32 v41, v14, v15
	v_pk_fma_f32 v[12:13], v[12:13], v[96:97], v[2:3]
	v_pk_fma_f32 v[14:15], v[14:15], v[98:99], v[4:5]
	s_waitcnt vmcnt(14)
	v_lshlrev_b32_e32 v2, 16, v44
	v_and_b32_e32 v3, 0xffff0000, v44
	v_lshlrev_b32_e32 v4, 16, v45
	v_and_b32_e32 v5, 0xffff0000, v45
	v_cvt_pk_bf16_f32 v42, v12, v13
	v_cvt_pk_bf16_f32 v43, v14, v15
	v_pk_fma_f32 v[12:13], v[12:13], v[100:101], v[2:3]
	v_pk_fma_f32 v[14:15], v[14:15], v[102:103], v[4:5]
	s_waitcnt vmcnt(12)
	v_lshlrev_b32_e32 v2, 16, v46
	v_and_b32_e32 v3, 0xffff0000, v46
	v_lshlrev_b32_e32 v4, 16, v47
	v_and_b32_e32 v5, 0xffff0000, v47
	v_cvt_pk_bf16_f32 v44, v12, v13
	v_cvt_pk_bf16_f32 v45, v14, v15
	v_pk_fma_f32 v[12:13], v[12:13], v[104:105], v[2:3]
	v_pk_fma_f32 v[14:15], v[14:15], v[106:107], v[4:5]
	s_waitcnt vmcnt(10)
	v_lshlrev_b32_e32 v2, 16, v48
	v_and_b32_e32 v3, 0xffff0000, v48
	v_lshlrev_b32_e32 v4, 16, v49
	v_and_b32_e32 v5, 0xffff0000, v49
	v_cvt_pk_bf16_f32 v46, v12, v13
	v_cvt_pk_bf16_f32 v47, v14, v15
	v_pk_fma_f32 v[12:13], v[12:13], v[108:109], v[2:3]
	v_pk_fma_f32 v[14:15], v[14:15], v[110:111], v[4:5]
	s_waitcnt vmcnt(8)
	v_lshlrev_b32_e32 v2, 16, v50
	v_and_b32_e32 v3, 0xffff0000, v50
	v_lshlrev_b32_e32 v4, 16, v51
	v_and_b32_e32 v5, 0xffff0000, v51
	v_cvt_pk_bf16_f32 v48, v12, v13
	v_cvt_pk_bf16_f32 v49, v14, v15
	v_pk_fma_f32 v[12:13], v[12:13], v[112:113], v[2:3]
	v_pk_fma_f32 v[14:15], v[14:15], v[114:115], v[4:5]
	s_waitcnt vmcnt(6)
	v_lshlrev_b32_e32 v2, 16, v52
	v_and_b32_e32 v3, 0xffff0000, v52
	v_lshlrev_b32_e32 v4, 16, v53
	v_and_b32_e32 v5, 0xffff0000, v53
	v_cvt_pk_bf16_f32 v50, v12, v13
	v_cvt_pk_bf16_f32 v51, v14, v15
	v_pk_fma_f32 v[12:13], v[12:13], v[116:117], v[2:3]
	v_pk_fma_f32 v[14:15], v[14:15], v[118:119], v[4:5]
	s_waitcnt vmcnt(4)
	v_lshlrev_b32_e32 v2, 16, v54
	v_and_b32_e32 v3, 0xffff0000, v54
	v_lshlrev_b32_e32 v4, 16, v55
	v_and_b32_e32 v5, 0xffff0000, v55
	v_cvt_pk_bf16_f32 v52, v12, v13
	v_cvt_pk_bf16_f32 v53, v14, v15
	v_pk_fma_f32 v[12:13], v[12:13], v[120:121], v[2:3]
	v_pk_fma_f32 v[14:15], v[14:15], v[122:123], v[4:5]
	s_waitcnt vmcnt(2)
	v_lshlrev_b32_e32 v2, 16, v56
	v_and_b32_e32 v3, 0xffff0000, v56
	v_lshlrev_b32_e32 v4, 16, v57
	v_and_b32_e32 v5, 0xffff0000, v57
	v_cvt_pk_bf16_f32 v54, v12, v13
	v_cvt_pk_bf16_f32 v55, v14, v15
	v_pk_fma_f32 v[12:13], v[12:13], v[124:125], v[2:3]
	v_pk_fma_f32 v[14:15], v[14:15], v[126:127], v[4:5]
	s_waitcnt vmcnt(0)
	v_lshlrev_b32_e32 v2, 16, v58
	v_and_b32_e32 v3, 0xffff0000, v58
	v_lshlrev_b32_e32 v4, 16, v59
	v_and_b32_e32 v5, 0xffff0000, v59
	v_cvt_pk_bf16_f32 v56, v12, v13
	v_cvt_pk_bf16_f32 v57, v14, v15
	v_pk_fma_f32 v[12:13], v[12:13], v[128:129], v[2:3]
	v_pk_fma_f32 v[14:15], v[14:15], v[130:131], v[4:5]
	v_mov_b32_e32 v22, v10
	v_mov_b32_e32 v23, v11
	global_store_dwordx2 v[22:23], v[6:7], off
	v_lshl_add_u64 v[22:23], v[22:23], 0, s[10:11]
	global_store_dwordx2 v[22:23], v[24:25], off
	v_lshl_add_u64 v[22:23], v[22:23], 0, s[10:11]
	global_store_dwordx2 v[22:23], v[26:27], off
	v_lshl_add_u64 v[22:23], v[22:23], 0, s[10:11]
	global_store_dwordx2 v[22:23], v[28:29], off
	v_lshl_add_u64 v[22:23], v[22:23], 0, s[10:11]
	global_store_dwordx2 v[22:23], v[30:31], off
	v_lshl_add_u64 v[22:23], v[22:23], 0, s[10:11]
	global_store_dwordx2 v[22:23], v[32:33], off
	v_lshl_add_u64 v[22:23], v[22:23], 0, s[10:11]
	global_store_dwordx2 v[22:23], v[34:35], off
	v_lshl_add_u64 v[22:23], v[22:23], 0, s[10:11]
	global_store_dwordx2 v[22:23], v[36:37], off
	v_lshl_add_u64 v[22:23], v[22:23], 0, s[10:11]
	global_store_dwordx2 v[22:23], v[38:39], off
	v_lshl_add_u64 v[22:23], v[22:23], 0, s[10:11]
	global_store_dwordx2 v[22:23], v[40:41], off
	v_lshl_add_u64 v[22:23], v[22:23], 0, s[10:11]
	global_store_dwordx2 v[22:23], v[42:43], off
	v_lshl_add_u64 v[22:23], v[22:23], 0, s[10:11]
	global_store_dwordx2 v[22:23], v[44:45], off
	v_lshl_add_u64 v[22:23], v[22:23], 0, s[10:11]
	global_store_dwordx2 v[22:23], v[46:47], off
	v_lshl_add_u64 v[22:23], v[22:23], 0, s[10:11]
	global_store_dwordx2 v[22:23], v[48:49], off
	v_lshl_add_u64 v[22:23], v[22:23], 0, s[10:11]
	global_store_dwordx2 v[22:23], v[50:51], off
	v_lshl_add_u64 v[22:23], v[22:23], 0, s[10:11]
	global_store_dwordx2 v[22:23], v[52:53], off
	v_lshl_add_u64 v[22:23], v[22:23], 0, s[10:11]
	global_store_dwordx2 v[22:23], v[54:55], off
	v_lshl_add_u64 v[22:23], v[22:23], 0, s[10:11]
	global_store_dwordx2 v[22:23], v[56:57], off
	v_lshl_add_u64 v[22:23], v[22:23], 0, s[10:11]
	v_mov_b32_e32 v10, v22
	v_mov_b32_e32 v11, v23
	s_mov_b64 s[12:13], 0x1200
	v_lshl_add_u64 v[8:9], v[8:9], 0, s[12:13]
	s_add_i32 s7, s7, 1
	s_cmp_lt_u32 s7, 2
	s_cbranch_scc1 .Lp2_batch
	v_add_u32_e32 v20, s6, v20
	s_mov_b32 s7, 0x1ffff
	v_cmp_lt_i32_e32 vcc, s7, v20
	s_or_b64 s[2:3], vcc, s[2:3]
	v_sub_u16_e32 v17, v17, v19
	s_andn2_b64 exec, exec, s[2:3]
	s_cbranch_execnz .LBB0_331
